# k22 plus: SwiGLU epilogues fold r^2 into the reciprocal input ((1+e)/r^2 by one packed fma), 40 fewer VALU per unit
# speedup vs baseline: 1.0020x; 1.0020x over previous
; __device__ __forceinline__ float rstd_of(float ss, float inv_n) { return __builtin_amdgcn_rsqf(ss * inv_n + 1e-6f); }
; __device__ __forceinline__ float sigmoid_f(float v) { return __builtin_amdgcn_rcpf(1.0f + __builtin_amdgcn_exp2f(-1.4426950408889634f * v)); }
; __device__ __forceinline__ u32x4 pack8(const f32x4 a, const f32x4 b) { u32x4 w; w.x = cvt_pk_bf16(a[0], a[1]); w.y = cvt_pk_bf16(a[2], a[3]); w.z = cvt_pk_bf16(b[0], b[1]); w.w = cvt_pk_bf16(b[2], b[3]); return w; }
;     __device__ __forceinline__ void operator()(f32x4 (&acc)[2][2][4][2], const Unit& u_, int wr, int wc, int fr, int fq) const {
;     ...
;                 const int row = row0 + ai * HALF + m * 16; const float r = rstd_of(sl[u.par * 256 + ai * HALF + wr * 64 + m * 16 + fr], 1.0f / 2048.0f) * ascale;
;                 f32x4 o[2];
; #pragma unroll
;                 for (int n = 0; n < 2; ++n) { const f32x4 g = acc[ai][0][m][n] * r, uu = acc[ai][1][m][n] * r;
; #pragma unroll
;                     for (int e = 0; e < 4; ++e) o[n][e] = g[e] * uu[e] * sigmoid_f(g[e]); }
;                 if constexpr (F8OUT) {
;                     typedef unsigned u32x2 __attribute__((ext_vector_type(2))); u32x2 w8; w8.x = pack4_fp8(o[0][0] * F8_ACT_SCALE, o[0][1] * F8_ACT_SCALE, o[0][2] * F8_ACT_SCALE, o[0][3] * F8_ACT_SCALE);
;                     w8.y = pack4_fp8(o[1][0] * F8_ACT_SCALE, o[1][1] * F8_ACT_SCALE, o[1][2] * F8_ACT_SCALE, o[1][3] * F8_ACT_SCALE);
;                     *(u32x2*)((unsigned char*)O + (((size_t)u.pm * (ldo / 128) + (col0 >> 7)) * BM + (ai * HALF + wr * 64 + m * 16 + fr)) * 128 + (col0 & 127)) = w8;
;                 } else
;                 *(u32x4*)(O + (((size_t)u.pm * (ldo / 64) + (col0 >> 6)) * BM + (ai * HALF + wr * 64 + m * 16 + fr)) * 64 + (col0 & 63)) = pack8(o[0], o[1]);
.LBB0_228:
	v_lshl_add_u32 v166, s76, 10, v162
	ds_read_b32 v172, v166
	ds_read_b32 v173, v166 offset:64
	ds_read_b32 v174, v166 offset:128
	ds_read_b32 v175, v166 offset:192
	ds_read_b32 v176, v166 offset:512
	ds_read_b32 v177, v166 offset:576
	ds_read_b32 v178, v166 offset:640
	ds_read_b32 v179, v166 offset:704
	v_lshl_add_u32 v167, s56, 7, v161
	s_andn2_b64 vcc, exec, s[6:7]
	s_mov_b64 s[6:7], -1
	v_ashrrev_i32_e32 v168, 6, v167
	v_ashrrev_i32_e32 v169, 31, v168
	v_mad_i64_i32 v[180:181], s[8:9], s54, v165, v[168:169]
	v_mov_b32_e32 v170, v152
	v_mov_b32_e32 v171, v129
	v_lshlrev_b64 v[180:181], 15, v[180:181]
	v_mov_b32_e32 v182, 1.0
	v_lshl_add_u64 v[180:181], s[34:35], 0, v[180:181]
	v_lshl_add_u64 v[180:181], v[180:181], 0, v[170:171]
	s_waitcnt lgkmcnt(0)
	v_fmamk_f32 v188, v172, 0x3a000000, v164
	v_rsq_f32_e32 v184, v188
	v_lshl_add_u64 v[202:203], v[180:181], 0, v[130:131]
	v_mul_f32_e32 v186, 0xbfb8aa3b, v184
	v_pk_mul_f32 v[190:191], v[124:125], v[186:187] op_sel_hi:[1,0]
	v_pk_mul_f32 v[192:193], v[126:127], v[186:187] op_sel_hi:[1,0]
	v_pk_mul_f32 v[124:125], v[124:125], v[120:121]
	v_exp_f32_e32 v190, v190
	v_exp_f32_e32 v191, v191
	v_exp_f32_e32 v192, v192
	v_exp_f32_e32 v193, v193
	v_pk_mul_f32 v[126:127], v[126:127], v[122:123]
	v_pk_fma_f32 v[190:191], v[190:191], v[188:189], v[188:189] op_sel_hi:[1,0,0]
	v_pk_fma_f32 v[192:193], v[192:193], v[188:189], v[188:189] op_sel_hi:[1,0,0]
	v_rcp_f32_e32 v190, v190
	v_rcp_f32_e32 v191, v191
	v_rcp_f32_e32 v192, v192
	v_rcp_f32_e32 v193, v193
	v_pk_mul_f32 v[124:125], v[124:125], v[190:191]
	v_pk_mul_f32 v[126:127], v[126:127], v[192:193]
	v_pk_mul_f32 v[190:191], v[116:117], v[186:187] op_sel_hi:[1,0]
	v_pk_mul_f32 v[192:193], v[118:119], v[186:187] op_sel_hi:[1,0]
	v_pk_mul_f32 v[116:117], v[116:117], v[112:113]
	v_exp_f32_e32 v190, v190
	v_exp_f32_e32 v191, v191
	v_exp_f32_e32 v192, v192
	v_exp_f32_e32 v193, v193
	v_pk_mul_f32 v[118:119], v[118:119], v[114:115]
	v_pk_fma_f32 v[190:191], v[190:191], v[188:189], v[188:189] op_sel_hi:[1,0,0]
	v_pk_fma_f32 v[192:193], v[192:193], v[188:189], v[188:189] op_sel_hi:[1,0,0]
	v_rcp_f32_e32 v190, v190
	v_rcp_f32_e32 v191, v191
	v_rcp_f32_e32 v192, v192
	v_rcp_f32_e32 v193, v193
	v_pk_mul_f32 v[116:117], v[116:117], v[190:191]
	v_pk_mul_f32 v[118:119], v[118:119], v[192:193]
	v_cvt_pk_bf16_f32 v194, v124, v125
	v_cvt_pk_bf16_f32 v195, v126, v127
	v_cvt_pk_bf16_f32 v196, v116, v117
	v_cvt_pk_bf16_f32 v197, v118, v119
	global_store_dwordx4 v[202:203], v[194:197], off
	v_fmamk_f32 v188, v173, 0x3a000000, v164
	v_rsq_f32_e32 v184, v188
	v_lshl_add_u64 v[202:203], v[180:181], 0, v[132:133]
	v_mul_f32_e32 v186, 0xbfb8aa3b, v184
	v_pk_mul_f32 v[190:191], v[108:109], v[186:187] op_sel_hi:[1,0]
	v_pk_mul_f32 v[192:193], v[110:111], v[186:187] op_sel_hi:[1,0]
	v_pk_mul_f32 v[108:109], v[108:109], v[104:105]
	v_exp_f32_e32 v190, v190
	v_exp_f32_e32 v191, v191
	v_exp_f32_e32 v192, v192
	v_exp_f32_e32 v193, v193
	v_pk_mul_f32 v[110:111], v[110:111], v[106:107]
	v_pk_fma_f32 v[190:191], v[190:191], v[188:189], v[188:189] op_sel_hi:[1,0,0]
	v_pk_fma_f32 v[192:193], v[192:193], v[188:189], v[188:189] op_sel_hi:[1,0,0]
	v_rcp_f32_e32 v190, v190
	v_rcp_f32_e32 v191, v191
	v_rcp_f32_e32 v192, v192
	v_rcp_f32_e32 v193, v193
	v_pk_mul_f32 v[108:109], v[108:109], v[190:191]
	v_pk_mul_f32 v[110:111], v[110:111], v[192:193]
	v_pk_mul_f32 v[190:191], v[100:101], v[186:187] op_sel_hi:[1,0]
	v_pk_mul_f32 v[192:193], v[102:103], v[186:187] op_sel_hi:[1,0]
	v_pk_mul_f32 v[100:101], v[100:101], v[96:97]
	v_exp_f32_e32 v190, v190
	v_exp_f32_e32 v191, v191
	v_exp_f32_e32 v192, v192
	v_exp_f32_e32 v193, v193
	v_pk_mul_f32 v[102:103], v[102:103], v[98:99]
	v_pk_fma_f32 v[190:191], v[190:191], v[188:189], v[188:189] op_sel_hi:[1,0,0]
	v_pk_fma_f32 v[192:193], v[192:193], v[188:189], v[188:189] op_sel_hi:[1,0,0]
	v_rcp_f32_e32 v190, v190
	v_rcp_f32_e32 v191, v191
	v_rcp_f32_e32 v192, v192
	v_rcp_f32_e32 v193, v193
	v_pk_mul_f32 v[100:101], v[100:101], v[190:191]
	v_pk_mul_f32 v[102:103], v[102:103], v[192:193]
	v_cvt_pk_bf16_f32 v198, v108, v109
	v_cvt_pk_bf16_f32 v199, v110, v111
	v_cvt_pk_bf16_f32 v200, v100, v101
	v_cvt_pk_bf16_f32 v201, v102, v103
	global_store_dwordx4 v[202:203], v[198:201], off
	v_fmamk_f32 v188, v174, 0x3a000000, v164
	v_rsq_f32_e32 v184, v188
	v_lshl_add_u64 v[202:203], v[180:181], 0, v[134:135]
	v_mul_f32_e32 v186, 0xbfb8aa3b, v184
	v_pk_mul_f32 v[190:191], v[92:93], v[186:187] op_sel_hi:[1,0]
	v_pk_mul_f32 v[192:193], v[94:95], v[186:187] op_sel_hi:[1,0]
	v_pk_mul_f32 v[92:93], v[92:93], v[88:89]
	v_exp_f32_e32 v190, v190
	v_exp_f32_e32 v191, v191
	v_exp_f32_e32 v192, v192
	v_exp_f32_e32 v193, v193
	v_pk_mul_f32 v[94:95], v[94:95], v[90:91]
	v_pk_fma_f32 v[190:191], v[190:191], v[188:189], v[188:189] op_sel_hi:[1,0,0]
	v_pk_fma_f32 v[192:193], v[192:193], v[188:189], v[188:189] op_sel_hi:[1,0,0]
	v_rcp_f32_e32 v190, v190
	v_rcp_f32_e32 v191, v191
	v_rcp_f32_e32 v192, v192
	v_rcp_f32_e32 v193, v193
	v_pk_mul_f32 v[92:93], v[92:93], v[190:191]
	v_pk_mul_f32 v[94:95], v[94:95], v[192:193]
	v_pk_mul_f32 v[190:191], v[84:85], v[186:187] op_sel_hi:[1,0]
	v_pk_mul_f32 v[192:193], v[86:87], v[186:187] op_sel_hi:[1,0]
	v_pk_mul_f32 v[84:85], v[84:85], v[80:81]
	v_exp_f32_e32 v190, v190
	v_exp_f32_e32 v191, v191
	v_exp_f32_e32 v192, v192
	v_exp_f32_e32 v193, v193
	v_pk_mul_f32 v[86:87], v[86:87], v[82:83]
	v_pk_fma_f32 v[190:191], v[190:191], v[188:189], v[188:189] op_sel_hi:[1,0,0]
	v_pk_fma_f32 v[192:193], v[192:193], v[188:189], v[188:189] op_sel_hi:[1,0,0]
	v_rcp_f32_e32 v190, v190
	v_rcp_f32_e32 v191, v191
	v_rcp_f32_e32 v192, v192
	v_rcp_f32_e32 v193, v193
; __device__ __forceinline__ float rstd_of(float ss, float inv_n) { return __builtin_amdgcn_rsqf(ss * inv_n + 1e-6f); }
; __device__ __forceinline__ float sigmoid_f(float v) { return __builtin_amdgcn_rcpf(1.0f + __builtin_amdgcn_exp2f(-1.4426950408889634f * v)); }
; __device__ __forceinline__ u32x4 pack8(const f32x4 a, const f32x4 b) { u32x4 w; w.x = cvt_pk_bf16(a[0], a[1]); w.y = cvt_pk_bf16(a[2], a[3]); w.z = cvt_pk_bf16(b[0], b[1]); w.w = cvt_pk_bf16(b[2], b[3]); return w; }
;     __device__ __forceinline__ void operator()(f32x4 (&acc)[2][2][4][2], const Unit& u_, int wr, int wc, int fr, int fq) const {
;     ...
;                 const int row = row0 + ai * HALF + m * 16; const float r = rstd_of(sl[u.par * 256 + ai * HALF + wr * 64 + m * 16 + fr], 1.0f / 2048.0f) * ascale;
;                 f32x4 o[2];
; #pragma unroll
;                 for (int n = 0; n < 2; ++n) { const f32x4 g = acc[ai][0][m][n] * r, uu = acc[ai][1][m][n] * r;
; #pragma unroll
;                     for (int e = 0; e < 4; ++e) o[n][e] = g[e] * uu[e] * sigmoid_f(g[e]); }
;                 if constexpr (F8OUT) {
;                     typedef unsigned u32x2 __attribute__((ext_vector_type(2))); u32x2 w8; w8.x = pack4_fp8(o[0][0] * F8_ACT_SCALE, o[0][1] * F8_ACT_SCALE, o[0][2] * F8_ACT_SCALE, o[0][3] * F8_ACT_SCALE);
;                     w8.y = pack4_fp8(o[1][0] * F8_ACT_SCALE, o[1][1] * F8_ACT_SCALE, o[1][2] * F8_ACT_SCALE, o[1][3] * F8_ACT_SCALE);
;                     *(u32x2*)((unsigned char*)O + (((size_t)u.pm * (ldo / 128) + (col0 >> 7)) * BM + (ai * HALF + wr * 64 + m * 16 + fr)) * 128 + (col0 & 127)) = w8;
;                 } else
;                 *(u32x4*)(O + (((size_t)u.pm * (ldo / 64) + (col0 >> 6)) * BM + (ai * HALF + wr * 64 + m * 16 + fr)) * 64 + (col0 & 63)) = pack8(o[0], o[1]);
	v_pk_mul_f32 v[84:85], v[84:85], v[190:191]
	v_pk_mul_f32 v[86:87], v[86:87], v[192:193]
	v_cvt_pk_bf16_f32 v194, v92, v93
	v_cvt_pk_bf16_f32 v195, v94, v95
	v_cvt_pk_bf16_f32 v196, v84, v85
	v_cvt_pk_bf16_f32 v197, v86, v87
	global_store_dwordx4 v[202:203], v[194:197], off
	v_fmamk_f32 v188, v175, 0x3a000000, v164
	v_rsq_f32_e32 v184, v188
	v_lshl_add_u64 v[202:203], v[180:181], 0, v[136:137]
	v_mul_f32_e32 v186, 0xbfb8aa3b, v184
	v_pk_mul_f32 v[190:191], v[76:77], v[186:187] op_sel_hi:[1,0]
	v_pk_mul_f32 v[192:193], v[78:79], v[186:187] op_sel_hi:[1,0]
	v_pk_mul_f32 v[76:77], v[76:77], v[72:73]
	v_exp_f32_e32 v190, v190
	v_exp_f32_e32 v191, v191
	v_exp_f32_e32 v192, v192
	v_exp_f32_e32 v193, v193
	v_pk_mul_f32 v[78:79], v[78:79], v[74:75]
	v_pk_fma_f32 v[190:191], v[190:191], v[188:189], v[188:189] op_sel_hi:[1,0,0]
	v_pk_fma_f32 v[192:193], v[192:193], v[188:189], v[188:189] op_sel_hi:[1,0,0]
	v_rcp_f32_e32 v190, v190
	v_rcp_f32_e32 v191, v191
	v_rcp_f32_e32 v192, v192
	v_rcp_f32_e32 v193, v193
	v_pk_mul_f32 v[76:77], v[76:77], v[190:191]
	v_pk_mul_f32 v[78:79], v[78:79], v[192:193]
	v_pk_mul_f32 v[190:191], v[68:69], v[186:187] op_sel_hi:[1,0]
	v_pk_mul_f32 v[192:193], v[70:71], v[186:187] op_sel_hi:[1,0]
	v_pk_mul_f32 v[68:69], v[68:69], v[64:65]
	v_exp_f32_e32 v190, v190
	v_exp_f32_e32 v191, v191
	v_exp_f32_e32 v192, v192
	v_exp_f32_e32 v193, v193
	v_pk_mul_f32 v[70:71], v[70:71], v[66:67]
	v_pk_fma_f32 v[190:191], v[190:191], v[188:189], v[188:189] op_sel_hi:[1,0,0]
	v_pk_fma_f32 v[192:193], v[192:193], v[188:189], v[188:189] op_sel_hi:[1,0,0]
	v_rcp_f32_e32 v190, v190
	v_rcp_f32_e32 v191, v191
	v_rcp_f32_e32 v192, v192
	v_rcp_f32_e32 v193, v193
	v_pk_mul_f32 v[68:69], v[68:69], v[190:191]
	v_pk_mul_f32 v[70:71], v[70:71], v[192:193]
	v_cvt_pk_bf16_f32 v198, v76, v77
	v_cvt_pk_bf16_f32 v199, v78, v79
	v_cvt_pk_bf16_f32 v200, v68, v69
	v_cvt_pk_bf16_f32 v201, v70, v71
	global_store_dwordx4 v[202:203], v[198:201], off
	v_fmamk_f32 v188, v176, 0x3a000000, v164
	v_rsq_f32_e32 v184, v188
	v_lshl_add_u64 v[202:203], v[180:181], 0, v[138:139]
	v_mul_f32_e32 v186, 0xbfb8aa3b, v184
	v_pk_mul_f32 v[190:191], v[60:61], v[186:187] op_sel_hi:[1,0]
	v_pk_mul_f32 v[192:193], v[62:63], v[186:187] op_sel_hi:[1,0]
	v_pk_mul_f32 v[60:61], v[60:61], v[56:57]
	v_exp_f32_e32 v190, v190
	v_exp_f32_e32 v191, v191
	v_exp_f32_e32 v192, v192
	v_exp_f32_e32 v193, v193
	v_pk_mul_f32 v[62:63], v[62:63], v[58:59]
	v_pk_fma_f32 v[190:191], v[190:191], v[188:189], v[188:189] op_sel_hi:[1,0,0]
	v_pk_fma_f32 v[192:193], v[192:193], v[188:189], v[188:189] op_sel_hi:[1,0,0]
	v_rcp_f32_e32 v190, v190
	v_rcp_f32_e32 v191, v191
	v_rcp_f32_e32 v192, v192
	v_rcp_f32_e32 v193, v193
	v_pk_mul_f32 v[60:61], v[60:61], v[190:191]
	v_pk_mul_f32 v[62:63], v[62:63], v[192:193]
	v_pk_mul_f32 v[190:191], v[52:53], v[186:187] op_sel_hi:[1,0]
	v_pk_mul_f32 v[192:193], v[54:55], v[186:187] op_sel_hi:[1,0]
	v_pk_mul_f32 v[52:53], v[52:53], v[48:49]
	v_exp_f32_e32 v190, v190
	v_exp_f32_e32 v191, v191
	v_exp_f32_e32 v192, v192
	v_exp_f32_e32 v193, v193
	v_pk_mul_f32 v[54:55], v[54:55], v[50:51]
	v_pk_fma_f32 v[190:191], v[190:191], v[188:189], v[188:189] op_sel_hi:[1,0,0]
	v_pk_fma_f32 v[192:193], v[192:193], v[188:189], v[188:189] op_sel_hi:[1,0,0]
	v_rcp_f32_e32 v190, v190
	v_rcp_f32_e32 v191, v191
	v_rcp_f32_e32 v192, v192
	v_rcp_f32_e32 v193, v193
	v_pk_mul_f32 v[52:53], v[52:53], v[190:191]
	v_pk_mul_f32 v[54:55], v[54:55], v[192:193]
	v_cvt_pk_bf16_f32 v194, v60, v61
	v_cvt_pk_bf16_f32 v195, v62, v63
	v_cvt_pk_bf16_f32 v196, v52, v53
	v_cvt_pk_bf16_f32 v197, v54, v55
	global_store_dwordx4 v[202:203], v[194:197], off
	v_fmamk_f32 v188, v177, 0x3a000000, v164
	v_rsq_f32_e32 v184, v188
	v_lshl_add_u64 v[202:203], v[180:181], 0, v[140:141]
	v_mul_f32_e32 v186, 0xbfb8aa3b, v184
	v_pk_mul_f32 v[190:191], v[44:45], v[186:187] op_sel_hi:[1,0]
	v_pk_mul_f32 v[192:193], v[46:47], v[186:187] op_sel_hi:[1,0]
	v_pk_mul_f32 v[44:45], v[44:45], v[40:41]
	v_exp_f32_e32 v190, v190
	v_exp_f32_e32 v191, v191
	v_exp_f32_e32 v192, v192
	v_exp_f32_e32 v193, v193
	v_pk_mul_f32 v[46:47], v[46:47], v[42:43]
	v_pk_fma_f32 v[190:191], v[190:191], v[188:189], v[188:189] op_sel_hi:[1,0,0]
	v_pk_fma_f32 v[192:193], v[192:193], v[188:189], v[188:189] op_sel_hi:[1,0,0]
	v_rcp_f32_e32 v190, v190
	v_rcp_f32_e32 v191, v191
	v_rcp_f32_e32 v192, v192
	v_rcp_f32_e32 v193, v193
; __device__ __forceinline__ float rstd_of(float ss, float inv_n) { return __builtin_amdgcn_rsqf(ss * inv_n + 1e-6f); }
; __device__ __forceinline__ float sigmoid_f(float v) { return __builtin_amdgcn_rcpf(1.0f + __builtin_amdgcn_exp2f(-1.4426950408889634f * v)); }
; __device__ __forceinline__ u32x4 pack8(const f32x4 a, const f32x4 b) { u32x4 w; w.x = cvt_pk_bf16(a[0], a[1]); w.y = cvt_pk_bf16(a[2], a[3]); w.z = cvt_pk_bf16(b[0], b[1]); w.w = cvt_pk_bf16(b[2], b[3]); return w; }
;     __device__ __forceinline__ void operator()(f32x4 (&acc)[2][2][4][2], const Unit& u_, int wr, int wc, int fr, int fq) const {
;     ...
;                 const int row = row0 + ai * HALF + m * 16; const float r = rstd_of(sl[u.par * 256 + ai * HALF + wr * 64 + m * 16 + fr], 1.0f / 2048.0f) * ascale;
;                 f32x4 o[2];
; #pragma unroll
;                 for (int n = 0; n < 2; ++n) { const f32x4 g = acc[ai][0][m][n] * r, uu = acc[ai][1][m][n] * r;
; #pragma unroll
;                     for (int e = 0; e < 4; ++e) o[n][e] = g[e] * uu[e] * sigmoid_f(g[e]); }
;                 if constexpr (F8OUT) {
;                     typedef unsigned u32x2 __attribute__((ext_vector_type(2))); u32x2 w8; w8.x = pack4_fp8(o[0][0] * F8_ACT_SCALE, o[0][1] * F8_ACT_SCALE, o[0][2] * F8_ACT_SCALE, o[0][3] * F8_ACT_SCALE);
;                     w8.y = pack4_fp8(o[1][0] * F8_ACT_SCALE, o[1][1] * F8_ACT_SCALE, o[1][2] * F8_ACT_SCALE, o[1][3] * F8_ACT_SCALE);
;                     *(u32x2*)((unsigned char*)O + (((size_t)u.pm * (ldo / 128) + (col0 >> 7)) * BM + (ai * HALF + wr * 64 + m * 16 + fr)) * 128 + (col0 & 127)) = w8;
;                 } else
;                 *(u32x4*)(O + (((size_t)u.pm * (ldo / 64) + (col0 >> 6)) * BM + (ai * HALF + wr * 64 + m * 16 + fr)) * 64 + (col0 & 63)) = pack8(o[0], o[1]);
	v_pk_mul_f32 v[44:45], v[44:45], v[190:191]
	v_pk_mul_f32 v[46:47], v[46:47], v[192:193]
	v_pk_mul_f32 v[190:191], v[36:37], v[186:187] op_sel_hi:[1,0]
	v_pk_mul_f32 v[192:193], v[38:39], v[186:187] op_sel_hi:[1,0]
	v_pk_mul_f32 v[36:37], v[36:37], v[32:33]
	v_exp_f32_e32 v190, v190
	v_exp_f32_e32 v191, v191
	v_exp_f32_e32 v192, v192
	v_exp_f32_e32 v193, v193
	v_pk_mul_f32 v[38:39], v[38:39], v[34:35]
	v_pk_fma_f32 v[190:191], v[190:191], v[188:189], v[188:189] op_sel_hi:[1,0,0]
	v_pk_fma_f32 v[192:193], v[192:193], v[188:189], v[188:189] op_sel_hi:[1,0,0]
	v_rcp_f32_e32 v190, v190
	v_rcp_f32_e32 v191, v191
	v_rcp_f32_e32 v192, v192
	v_rcp_f32_e32 v193, v193
	v_pk_mul_f32 v[36:37], v[36:37], v[190:191]
	v_pk_mul_f32 v[38:39], v[38:39], v[192:193]
	v_cvt_pk_bf16_f32 v198, v44, v45
	v_cvt_pk_bf16_f32 v199, v46, v47
	v_cvt_pk_bf16_f32 v200, v36, v37
	v_cvt_pk_bf16_f32 v201, v38, v39
	global_store_dwordx4 v[202:203], v[198:201], off
	v_fmamk_f32 v188, v178, 0x3a000000, v164
	v_rsq_f32_e32 v184, v188
	v_lshl_add_u64 v[202:203], v[180:181], 0, v[142:143]
	v_mul_f32_e32 v186, 0xbfb8aa3b, v184
	v_pk_mul_f32 v[190:191], v[28:29], v[186:187] op_sel_hi:[1,0]
	v_pk_mul_f32 v[192:193], v[30:31], v[186:187] op_sel_hi:[1,0]
	v_pk_mul_f32 v[28:29], v[28:29], v[24:25]
	v_exp_f32_e32 v190, v190
	v_exp_f32_e32 v191, v191
	v_exp_f32_e32 v192, v192
	v_exp_f32_e32 v193, v193
	v_pk_mul_f32 v[30:31], v[30:31], v[26:27]
	v_pk_fma_f32 v[190:191], v[190:191], v[188:189], v[188:189] op_sel_hi:[1,0,0]
	v_pk_fma_f32 v[192:193], v[192:193], v[188:189], v[188:189] op_sel_hi:[1,0,0]
	v_rcp_f32_e32 v190, v190
	v_rcp_f32_e32 v191, v191
	v_rcp_f32_e32 v192, v192
	v_rcp_f32_e32 v193, v193
	v_pk_mul_f32 v[28:29], v[28:29], v[190:191]
	v_pk_mul_f32 v[30:31], v[30:31], v[192:193]
	v_pk_mul_f32 v[190:191], v[20:21], v[186:187] op_sel_hi:[1,0]
	v_pk_mul_f32 v[192:193], v[22:23], v[186:187] op_sel_hi:[1,0]
	v_pk_mul_f32 v[20:21], v[20:21], v[16:17]
	v_exp_f32_e32 v190, v190
	v_exp_f32_e32 v191, v191
	v_exp_f32_e32 v192, v192
	v_exp_f32_e32 v193, v193
	v_pk_mul_f32 v[22:23], v[22:23], v[18:19]
	v_pk_fma_f32 v[190:191], v[190:191], v[188:189], v[188:189] op_sel_hi:[1,0,0]
	v_pk_fma_f32 v[192:193], v[192:193], v[188:189], v[188:189] op_sel_hi:[1,0,0]
	v_rcp_f32_e32 v190, v190
	v_rcp_f32_e32 v191, v191
	v_rcp_f32_e32 v192, v192
	v_rcp_f32_e32 v193, v193
	v_pk_mul_f32 v[20:21], v[20:21], v[190:191]
	v_pk_mul_f32 v[22:23], v[22:23], v[192:193]
	v_cvt_pk_bf16_f32 v194, v28, v29
	v_cvt_pk_bf16_f32 v195, v30, v31
	v_cvt_pk_bf16_f32 v196, v20, v21
	v_cvt_pk_bf16_f32 v197, v22, v23
	global_store_dwordx4 v[202:203], v[194:197], off
	v_fmamk_f32 v188, v179, 0x3a000000, v164
	v_rsq_f32_e32 v184, v188
	v_lshl_add_u64 v[202:203], v[180:181], 0, v[144:145]
	v_mul_f32_e32 v186, 0xbfb8aa3b, v184
	v_pk_mul_f32 v[190:191], v[12:13], v[186:187] op_sel_hi:[1,0]
	v_pk_mul_f32 v[192:193], v[14:15], v[186:187] op_sel_hi:[1,0]
	v_pk_mul_f32 v[12:13], v[12:13], v[8:9]
	v_exp_f32_e32 v190, v190
	v_exp_f32_e32 v191, v191
	v_exp_f32_e32 v192, v192
	v_exp_f32_e32 v193, v193
	v_pk_mul_f32 v[14:15], v[14:15], v[10:11]
	v_pk_fma_f32 v[190:191], v[190:191], v[188:189], v[188:189] op_sel_hi:[1,0,0]
	v_pk_fma_f32 v[192:193], v[192:193], v[188:189], v[188:189] op_sel_hi:[1,0,0]
	v_rcp_f32_e32 v190, v190
	v_rcp_f32_e32 v191, v191
	v_rcp_f32_e32 v192, v192
	v_rcp_f32_e32 v193, v193
	v_pk_mul_f32 v[12:13], v[12:13], v[190:191]
	v_pk_mul_f32 v[14:15], v[14:15], v[192:193]
	v_pk_mul_f32 v[190:191], v[4:5], v[186:187] op_sel_hi:[1,0]
	v_pk_mul_f32 v[192:193], v[6:7], v[186:187] op_sel_hi:[1,0]
	v_pk_mul_f32 v[4:5], v[4:5], v[0:1]
	v_exp_f32_e32 v190, v190
	v_exp_f32_e32 v191, v191
	v_exp_f32_e32 v192, v192
	v_exp_f32_e32 v193, v193
	v_pk_mul_f32 v[6:7], v[6:7], v[2:3]
	v_pk_fma_f32 v[190:191], v[190:191], v[188:189], v[188:189] op_sel_hi:[1,0,0]
	v_pk_fma_f32 v[192:193], v[192:193], v[188:189], v[188:189] op_sel_hi:[1,0,0]
	v_rcp_f32_e32 v190, v190
	v_rcp_f32_e32 v191, v191
	v_rcp_f32_e32 v192, v192
	v_rcp_f32_e32 v193, v193
	v_pk_mul_f32 v[4:5], v[4:5], v[190:191]
	v_pk_mul_f32 v[6:7], v[6:7], v[192:193]
	v_cvt_pk_bf16_f32 v198, v12, v13
	v_cvt_pk_bf16_f32 v199, v14, v15
	v_cvt_pk_bf16_f32 v200, v4, v5
	v_cvt_pk_bf16_f32 v201, v6, v7
	global_store_dwordx4 v[202:203], v[198:201], off
	s_cbranch_vccnz .LBB0_219
	s_and_b64 vcc, exec, s[10:11]
	s_cbranch_vccnz .LBB0_218
	s_barrier
	s_branch .LBB0_218

; __device__ __forceinline__ float rstd_of(float ss, float inv_n) { return __builtin_amdgcn_rsqf(ss * inv_n + 1e-6f); }
; __device__ __forceinline__ float sigmoid_f(float v) { return __builtin_amdgcn_rcpf(1.0f + __builtin_amdgcn_exp2f(-1.4426950408889634f * v)); }
; __device__ __forceinline__ u32x4 pack8(const f32x4 a, const f32x4 b) { u32x4 w; w.x = cvt_pk_bf16(a[0], a[1]); w.y = cvt_pk_bf16(a[2], a[3]); w.z = cvt_pk_bf16(b[0], b[1]); w.w = cvt_pk_bf16(b[2], b[3]); return w; }
;     __device__ __forceinline__ void operator()(f32x4 (&acc)[2][2][4][2], const Unit& u_, int wr, int wc, int fr, int fq) const {
;         Unit u = u_; if constexpr (OPQ) { unsigned o1_ = ~0u; asm volatile("" : "+s"(u.pm), "+s"(u.pn), "+s"(o1_)); const int l_ = (int)__builtin_amdgcn_mbcnt_hi(o1_, __builtin_amdgcn_mbcnt_lo(o1_, 0u)); fr = l_ & 15; fq = l_ >> 4; }
;         const int row0 = u.pm * BM + wr * 64 + fr, col0 = u.pn * HALF + wc * 32 + 8 * fq;
; #pragma unroll
;         for (int ai = 0; ai < 2; ++ai)
; #pragma unroll
;             for (int m = 0; m < 4; ++m) {
;                 const int row = row0 + ai * HALF + m * 16; const float r = rstd_of(sl[u.par * 256 + ai * HALF + wr * 64 + m * 16 + fr], 1.0f / 2048.0f) * ascale;
;                 f32x4 o[2];
; #pragma unroll
;                 for (int n = 0; n < 2; ++n) { const f32x4 g = acc[ai][0][m][n] * r, uu = acc[ai][1][m][n] * r;
; #pragma unroll
;                     for (int e = 0; e < 4; ++e) o[n][e] = g[e] * uu[e] * sigmoid_f(g[e]); }
;                 if constexpr (F8OUT) {
;                     typedef unsigned u32x2 __attribute__((ext_vector_type(2))); u32x2 w8; w8.x = pack4_fp8(o[0][0] * F8_ACT_SCALE, o[0][1] * F8_ACT_SCALE, o[0][2] * F8_ACT_SCALE, o[0][3] * F8_ACT_SCALE);
;                     w8.y = pack4_fp8(o[1][0] * F8_ACT_SCALE, o[1][1] * F8_ACT_SCALE, o[1][2] * F8_ACT_SCALE, o[1][3] * F8_ACT_SCALE);
;                     *(u32x2*)((unsigned char*)O + (((size_t)u.pm * (ldo / 128) + (col0 >> 7)) * BM + (ai * HALF + wr * 64 + m * 16 + fr)) * 128 + (col0 & 127)) = w8;
;                 } else
;                 *(u32x4*)(O + (((size_t)u.pm * (ldo / 64) + (col0 >> 6)) * BM + (ai * HALF + wr * 64 + m * 16 + fr)) * 64 + (col0 & 63)) = pack8(o[0], o[1]);
.LBB0_815:
	s_lshl_b32 s11, s65, 10
	v_mbcnt_lo_u32_b32 v168, -1, 0
	v_mbcnt_hi_u32_b32 v168, -1, v168
	s_add_i32 s11, s53, s11
	v_and_b32_e32 v169, 15, v168
	v_lshl_add_u32 v166, v169, 2, s11
	ds_read_b32 v172, v166
	ds_read_b32 v173, v166 offset:64
	ds_read_b32 v174, v166 offset:128
	ds_read_b32 v175, v166 offset:192
	ds_read_b32 v176, v166 offset:512
	ds_read_b32 v177, v166 offset:576
	ds_read_b32 v178, v166 offset:640
	ds_read_b32 v179, v166 offset:704
	s_lshl_b32 s10, s52, 7
	v_lshrrev_b32_e32 v168, 1, v168
	s_or_b32 s10, s10, s91
	v_and_b32_e32 v168, 56, v168
	v_add_u32_e32 v167, s10, v168
	s_andn2_b64 vcc, exec, s[8:9]
	s_mov_b64 s[8:9], -1
	v_or_b32_e32 v170, s94, v169
	v_mov_b32_e32 v171, 0
	v_ashrrev_i32_e32 v168, 6, v167
	v_ashrrev_i32_e32 v169, 31, v168
	v_mad_i64_i32 v[180:181], s[10:11], s50, v146, v[168:169]
	v_lshlrev_b64 v[170:171], 7, v[170:171]
	v_lshlrev_b64 v[180:181], 15, v[180:181]
	v_and_b32_e32 v168, 56, v167
	v_lshl_add_u64 v[180:181], s[34:35], 0, v[180:181]
	v_lshlrev_b32_e32 v168, 1, v168
	v_mov_b32_e32 v169, 0
	v_lshl_add_u64 v[180:181], v[180:181], 0, v[170:171]
	v_mov_b32_e32 v182, 1.0
	v_lshl_add_u64 v[180:181], v[180:181], 0, v[168:169]
	s_mov_b64 s[10:11], 0x1000
	v_lshl_add_u64 v[202:203], v[180:181], 0, s[10:11]
	s_mov_b64 s[10:11], 0x5000
	v_lshl_add_u64 v[204:205], v[180:181], 0, s[10:11]
	s_waitcnt lgkmcnt(0)
	v_fmamk_f32 v188, v172, 0x3a000000, v145
	v_rsq_f32_e32 v184, v188
	s_nop 0
	v_mul_f32_e32 v184, 0x3a800000, v184
	v_mul_f32_e32 v186, 0xbfb8aa3b, v184
	v_mul_f32_e32 v188, 0x49800000, v188
	v_pk_mul_f32 v[190:191], v[124:125], v[186:187] op_sel_hi:[1,0]
	v_pk_mul_f32 v[192:193], v[126:127], v[186:187] op_sel_hi:[1,0]
	v_pk_mul_f32 v[124:125], v[124:125], v[120:121]
	v_exp_f32_e32 v190, v190
	v_exp_f32_e32 v191, v191
	v_exp_f32_e32 v192, v192
	v_exp_f32_e32 v193, v193
	v_pk_mul_f32 v[126:127], v[126:127], v[122:123]
	v_pk_fma_f32 v[190:191], v[190:191], v[188:189], v[188:189] op_sel_hi:[1,0,0]
	v_pk_fma_f32 v[192:193], v[192:193], v[188:189], v[188:189] op_sel_hi:[1,0,0]
	v_rcp_f32_e32 v190, v190
	v_rcp_f32_e32 v191, v191
	v_rcp_f32_e32 v192, v192
	v_rcp_f32_e32 v193, v193
	v_pk_mul_f32 v[124:125], v[124:125], v[190:191]
	v_pk_mul_f32 v[126:127], v[126:127], v[192:193]
	v_pk_mul_f32 v[190:191], v[116:117], v[186:187] op_sel_hi:[1,0]
	v_pk_mul_f32 v[192:193], v[118:119], v[186:187] op_sel_hi:[1,0]
	v_pk_mul_f32 v[116:117], v[116:117], v[112:113]
	v_exp_f32_e32 v190, v190
	v_exp_f32_e32 v191, v191
	v_exp_f32_e32 v192, v192
	v_exp_f32_e32 v193, v193
	v_pk_mul_f32 v[118:119], v[118:119], v[114:115]
	v_pk_fma_f32 v[190:191], v[190:191], v[188:189], v[188:189] op_sel_hi:[1,0,0]
	v_pk_fma_f32 v[192:193], v[192:193], v[188:189], v[188:189] op_sel_hi:[1,0,0]
	v_rcp_f32_e32 v190, v190
	v_rcp_f32_e32 v191, v191
	v_rcp_f32_e32 v192, v192
	v_rcp_f32_e32 v193, v193
	v_pk_mul_f32 v[116:117], v[116:117], v[190:191]
	v_pk_mul_f32 v[118:119], v[118:119], v[192:193]
	v_cvt_pk_bf16_f32 v194, v124, v125
	v_cvt_pk_bf16_f32 v195, v126, v127
	v_cvt_pk_bf16_f32 v196, v116, v117
	v_cvt_pk_bf16_f32 v197, v118, v119
	global_store_dwordx4 v[202:203], v[194:197], off offset:-4096
	v_fmamk_f32 v188, v173, 0x3a000000, v145
	v_rsq_f32_e32 v184, v188
	s_nop 0
	v_mul_f32_e32 v184, 0x3a800000, v184
	v_mul_f32_e32 v186, 0xbfb8aa3b, v184
	v_mul_f32_e32 v188, 0x49800000, v188
	v_pk_mul_f32 v[190:191], v[108:109], v[186:187] op_sel_hi:[1,0]
	v_pk_mul_f32 v[192:193], v[110:111], v[186:187] op_sel_hi:[1,0]
	v_pk_mul_f32 v[108:109], v[108:109], v[104:105]
	v_exp_f32_e32 v190, v190
	v_exp_f32_e32 v191, v191
	v_exp_f32_e32 v192, v192
	v_exp_f32_e32 v193, v193
	v_pk_mul_f32 v[110:111], v[110:111], v[106:107]
	v_pk_fma_f32 v[190:191], v[190:191], v[188:189], v[188:189] op_sel_hi:[1,0,0]
	v_pk_fma_f32 v[192:193], v[192:193], v[188:189], v[188:189] op_sel_hi:[1,0,0]
	v_rcp_f32_e32 v190, v190
	v_rcp_f32_e32 v191, v191
	v_rcp_f32_e32 v192, v192
	v_rcp_f32_e32 v193, v193
	v_pk_mul_f32 v[108:109], v[108:109], v[190:191]
	v_pk_mul_f32 v[110:111], v[110:111], v[192:193]
	v_pk_mul_f32 v[190:191], v[100:101], v[186:187] op_sel_hi:[1,0]
	v_pk_mul_f32 v[192:193], v[102:103], v[186:187] op_sel_hi:[1,0]
	v_pk_mul_f32 v[100:101], v[100:101], v[96:97]
	v_exp_f32_e32 v190, v190
	v_exp_f32_e32 v191, v191
	v_exp_f32_e32 v192, v192
	v_exp_f32_e32 v193, v193
	v_pk_mul_f32 v[102:103], v[102:103], v[98:99]
	v_pk_fma_f32 v[190:191], v[190:191], v[188:189], v[188:189] op_sel_hi:[1,0,0]
	v_pk_fma_f32 v[192:193], v[192:193], v[188:189], v[188:189] op_sel_hi:[1,0,0]
	v_rcp_f32_e32 v190, v190
	v_rcp_f32_e32 v191, v191
	v_rcp_f32_e32 v192, v192
	v_rcp_f32_e32 v193, v193
	v_pk_mul_f32 v[100:101], v[100:101], v[190:191]
	v_pk_mul_f32 v[102:103], v[102:103], v[192:193]
	v_cvt_pk_bf16_f32 v198, v108, v109
	v_cvt_pk_bf16_f32 v199, v110, v111
	v_cvt_pk_bf16_f32 v200, v100, v101
	v_cvt_pk_bf16_f32 v201, v102, v103
	global_store_dwordx4 v[202:203], v[198:201], off offset:-2048
	v_fmamk_f32 v188, v174, 0x3a000000, v145
	v_rsq_f32_e32 v184, v188
	s_nop 0
	v_mul_f32_e32 v184, 0x3a800000, v184
	v_mul_f32_e32 v186, 0xbfb8aa3b, v184
	v_mul_f32_e32 v188, 0x49800000, v188
	v_pk_mul_f32 v[190:191], v[92:93], v[186:187] op_sel_hi:[1,0]
	v_pk_mul_f32 v[192:193], v[94:95], v[186:187] op_sel_hi:[1,0]
	v_pk_mul_f32 v[92:93], v[92:93], v[88:89]
	v_exp_f32_e32 v190, v190
	v_exp_f32_e32 v191, v191
	v_exp_f32_e32 v192, v192
	v_exp_f32_e32 v193, v193
	v_pk_mul_f32 v[94:95], v[94:95], v[90:91]
	v_pk_fma_f32 v[190:191], v[190:191], v[188:189], v[188:189] op_sel_hi:[1,0,0]
	v_pk_fma_f32 v[192:193], v[192:193], v[188:189], v[188:189] op_sel_hi:[1,0,0]
	v_rcp_f32_e32 v190, v190
	v_rcp_f32_e32 v191, v191
; __device__ __forceinline__ float rstd_of(float ss, float inv_n) { return __builtin_amdgcn_rsqf(ss * inv_n + 1e-6f); }
; __device__ __forceinline__ float sigmoid_f(float v) { return __builtin_amdgcn_rcpf(1.0f + __builtin_amdgcn_exp2f(-1.4426950408889634f * v)); }
; __device__ __forceinline__ u32x4 pack8(const f32x4 a, const f32x4 b) { u32x4 w; w.x = cvt_pk_bf16(a[0], a[1]); w.y = cvt_pk_bf16(a[2], a[3]); w.z = cvt_pk_bf16(b[0], b[1]); w.w = cvt_pk_bf16(b[2], b[3]); return w; }
;     __device__ __forceinline__ void operator()(f32x4 (&acc)[2][2][4][2], const Unit& u_, int wr, int wc, int fr, int fq) const {
;     ...
;                 const int row = row0 + ai * HALF + m * 16; const float r = rstd_of(sl[u.par * 256 + ai * HALF + wr * 64 + m * 16 + fr], 1.0f / 2048.0f) * ascale;
;                 f32x4 o[2];
; #pragma unroll
;                 for (int n = 0; n < 2; ++n) { const f32x4 g = acc[ai][0][m][n] * r, uu = acc[ai][1][m][n] * r;
; #pragma unroll
;                     for (int e = 0; e < 4; ++e) o[n][e] = g[e] * uu[e] * sigmoid_f(g[e]); }
;                 if constexpr (F8OUT) {
;                     typedef unsigned u32x2 __attribute__((ext_vector_type(2))); u32x2 w8; w8.x = pack4_fp8(o[0][0] * F8_ACT_SCALE, o[0][1] * F8_ACT_SCALE, o[0][2] * F8_ACT_SCALE, o[0][3] * F8_ACT_SCALE);
;                     w8.y = pack4_fp8(o[1][0] * F8_ACT_SCALE, o[1][1] * F8_ACT_SCALE, o[1][2] * F8_ACT_SCALE, o[1][3] * F8_ACT_SCALE);
;                     *(u32x2*)((unsigned char*)O + (((size_t)u.pm * (ldo / 128) + (col0 >> 7)) * BM + (ai * HALF + wr * 64 + m * 16 + fr)) * 128 + (col0 & 127)) = w8;
;                 } else
;                 *(u32x4*)(O + (((size_t)u.pm * (ldo / 64) + (col0 >> 6)) * BM + (ai * HALF + wr * 64 + m * 16 + fr)) * 64 + (col0 & 63)) = pack8(o[0], o[1]);
	v_rcp_f32_e32 v192, v192
	v_rcp_f32_e32 v193, v193
	v_pk_mul_f32 v[92:93], v[92:93], v[190:191]
	v_pk_mul_f32 v[94:95], v[94:95], v[192:193]
	v_pk_mul_f32 v[190:191], v[84:85], v[186:187] op_sel_hi:[1,0]
	v_pk_mul_f32 v[192:193], v[86:87], v[186:187] op_sel_hi:[1,0]
	v_pk_mul_f32 v[84:85], v[84:85], v[80:81]
	v_exp_f32_e32 v190, v190
	v_exp_f32_e32 v191, v191
	v_exp_f32_e32 v192, v192
	v_exp_f32_e32 v193, v193
	v_pk_mul_f32 v[86:87], v[86:87], v[82:83]
	v_pk_fma_f32 v[190:191], v[190:191], v[188:189], v[188:189] op_sel_hi:[1,0,0]
	v_pk_fma_f32 v[192:193], v[192:193], v[188:189], v[188:189] op_sel_hi:[1,0,0]
	v_rcp_f32_e32 v190, v190
	v_rcp_f32_e32 v191, v191
	v_rcp_f32_e32 v192, v192
	v_rcp_f32_e32 v193, v193
	v_pk_mul_f32 v[84:85], v[84:85], v[190:191]
	v_pk_mul_f32 v[86:87], v[86:87], v[192:193]
	v_cvt_pk_bf16_f32 v194, v92, v93
	v_cvt_pk_bf16_f32 v195, v94, v95
	v_cvt_pk_bf16_f32 v196, v84, v85
	v_cvt_pk_bf16_f32 v197, v86, v87
	global_store_dwordx4 v[202:203], v[194:197], off offset:0
	v_fmamk_f32 v188, v175, 0x3a000000, v145
	v_rsq_f32_e32 v184, v188
	s_nop 0
	v_mul_f32_e32 v184, 0x3a800000, v184
	v_mul_f32_e32 v186, 0xbfb8aa3b, v184
	v_mul_f32_e32 v188, 0x49800000, v188
	v_pk_mul_f32 v[190:191], v[76:77], v[186:187] op_sel_hi:[1,0]
	v_pk_mul_f32 v[192:193], v[78:79], v[186:187] op_sel_hi:[1,0]
	v_pk_mul_f32 v[76:77], v[76:77], v[72:73]
	v_exp_f32_e32 v190, v190
	v_exp_f32_e32 v191, v191
	v_exp_f32_e32 v192, v192
	v_exp_f32_e32 v193, v193
	v_pk_mul_f32 v[78:79], v[78:79], v[74:75]
	v_pk_fma_f32 v[190:191], v[190:191], v[188:189], v[188:189] op_sel_hi:[1,0,0]
	v_pk_fma_f32 v[192:193], v[192:193], v[188:189], v[188:189] op_sel_hi:[1,0,0]
	v_rcp_f32_e32 v190, v190
	v_rcp_f32_e32 v191, v191
	v_rcp_f32_e32 v192, v192
	v_rcp_f32_e32 v193, v193
	v_pk_mul_f32 v[76:77], v[76:77], v[190:191]
	v_pk_mul_f32 v[78:79], v[78:79], v[192:193]
	v_pk_mul_f32 v[190:191], v[68:69], v[186:187] op_sel_hi:[1,0]
	v_pk_mul_f32 v[192:193], v[70:71], v[186:187] op_sel_hi:[1,0]
	v_pk_mul_f32 v[68:69], v[68:69], v[64:65]
	v_exp_f32_e32 v190, v190
	v_exp_f32_e32 v191, v191
	v_exp_f32_e32 v192, v192
	v_exp_f32_e32 v193, v193
	v_pk_mul_f32 v[70:71], v[70:71], v[66:67]
	v_pk_fma_f32 v[190:191], v[190:191], v[188:189], v[188:189] op_sel_hi:[1,0,0]
	v_pk_fma_f32 v[192:193], v[192:193], v[188:189], v[188:189] op_sel_hi:[1,0,0]
	v_rcp_f32_e32 v190, v190
	v_rcp_f32_e32 v191, v191
	v_rcp_f32_e32 v192, v192
	v_rcp_f32_e32 v193, v193
	v_pk_mul_f32 v[68:69], v[68:69], v[190:191]
	v_pk_mul_f32 v[70:71], v[70:71], v[192:193]
	v_cvt_pk_bf16_f32 v198, v76, v77
	v_cvt_pk_bf16_f32 v199, v78, v79
	v_cvt_pk_bf16_f32 v200, v68, v69
	v_cvt_pk_bf16_f32 v201, v70, v71
	global_store_dwordx4 v[202:203], v[198:201], off offset:2048
	v_fmamk_f32 v188, v176, 0x3a000000, v145
	v_rsq_f32_e32 v184, v188
	s_nop 0
	v_mul_f32_e32 v184, 0x3a800000, v184
	v_mul_f32_e32 v186, 0xbfb8aa3b, v184
	v_mul_f32_e32 v188, 0x49800000, v188
	v_pk_mul_f32 v[190:191], v[60:61], v[186:187] op_sel_hi:[1,0]
	v_pk_mul_f32 v[192:193], v[62:63], v[186:187] op_sel_hi:[1,0]
	v_pk_mul_f32 v[60:61], v[60:61], v[56:57]
	v_exp_f32_e32 v190, v190
	v_exp_f32_e32 v191, v191
	v_exp_f32_e32 v192, v192
	v_exp_f32_e32 v193, v193
	v_pk_mul_f32 v[62:63], v[62:63], v[58:59]
	v_pk_fma_f32 v[190:191], v[190:191], v[188:189], v[188:189] op_sel_hi:[1,0,0]
	v_pk_fma_f32 v[192:193], v[192:193], v[188:189], v[188:189] op_sel_hi:[1,0,0]
	v_rcp_f32_e32 v190, v190
	v_rcp_f32_e32 v191, v191
	v_rcp_f32_e32 v192, v192
	v_rcp_f32_e32 v193, v193
	v_pk_mul_f32 v[60:61], v[60:61], v[190:191]
	v_pk_mul_f32 v[62:63], v[62:63], v[192:193]
	v_pk_mul_f32 v[190:191], v[52:53], v[186:187] op_sel_hi:[1,0]
	v_pk_mul_f32 v[192:193], v[54:55], v[186:187] op_sel_hi:[1,0]
	v_pk_mul_f32 v[52:53], v[52:53], v[48:49]
	v_exp_f32_e32 v190, v190
	v_exp_f32_e32 v191, v191
	v_exp_f32_e32 v192, v192
	v_exp_f32_e32 v193, v193
	v_pk_mul_f32 v[54:55], v[54:55], v[50:51]
	v_pk_fma_f32 v[190:191], v[190:191], v[188:189], v[188:189] op_sel_hi:[1,0,0]
	v_pk_fma_f32 v[192:193], v[192:193], v[188:189], v[188:189] op_sel_hi:[1,0,0]
	v_rcp_f32_e32 v190, v190
	v_rcp_f32_e32 v191, v191
	v_rcp_f32_e32 v192, v192
	v_rcp_f32_e32 v193, v193
	v_pk_mul_f32 v[52:53], v[52:53], v[190:191]
	v_pk_mul_f32 v[54:55], v[54:55], v[192:193]
	v_cvt_pk_bf16_f32 v194, v60, v61
	v_cvt_pk_bf16_f32 v195, v62, v63
	v_cvt_pk_bf16_f32 v196, v52, v53
	v_cvt_pk_bf16_f32 v197, v54, v55
	global_store_dwordx4 v[204:205], v[194:197], off offset:-4096
	v_fmamk_f32 v188, v177, 0x3a000000, v145
	v_rsq_f32_e32 v184, v188
	s_nop 0
	v_mul_f32_e32 v184, 0x3a800000, v184
	v_mul_f32_e32 v186, 0xbfb8aa3b, v184
	v_mul_f32_e32 v188, 0x49800000, v188
	v_pk_mul_f32 v[190:191], v[44:45], v[186:187] op_sel_hi:[1,0]
	v_pk_mul_f32 v[192:193], v[46:47], v[186:187] op_sel_hi:[1,0]
	v_pk_mul_f32 v[44:45], v[44:45], v[40:41]
	v_exp_f32_e32 v190, v190
	v_exp_f32_e32 v191, v191
; __device__ __forceinline__ float rstd_of(float ss, float inv_n) { return __builtin_amdgcn_rsqf(ss * inv_n + 1e-6f); }
; __device__ __forceinline__ float sigmoid_f(float v) { return __builtin_amdgcn_rcpf(1.0f + __builtin_amdgcn_exp2f(-1.4426950408889634f * v)); }
; __device__ __forceinline__ u32x4 pack8(const f32x4 a, const f32x4 b) { u32x4 w; w.x = cvt_pk_bf16(a[0], a[1]); w.y = cvt_pk_bf16(a[2], a[3]); w.z = cvt_pk_bf16(b[0], b[1]); w.w = cvt_pk_bf16(b[2], b[3]); return w; }
;     __device__ __forceinline__ void operator()(f32x4 (&acc)[2][2][4][2], const Unit& u_, int wr, int wc, int fr, int fq) const {
;     ...
;                 const int row = row0 + ai * HALF + m * 16; const float r = rstd_of(sl[u.par * 256 + ai * HALF + wr * 64 + m * 16 + fr], 1.0f / 2048.0f) * ascale;
;                 f32x4 o[2];
; #pragma unroll
;                 for (int n = 0; n < 2; ++n) { const f32x4 g = acc[ai][0][m][n] * r, uu = acc[ai][1][m][n] * r;
; #pragma unroll
;                     for (int e = 0; e < 4; ++e) o[n][e] = g[e] * uu[e] * sigmoid_f(g[e]); }
;                 if constexpr (F8OUT) {
;                     typedef unsigned u32x2 __attribute__((ext_vector_type(2))); u32x2 w8; w8.x = pack4_fp8(o[0][0] * F8_ACT_SCALE, o[0][1] * F8_ACT_SCALE, o[0][2] * F8_ACT_SCALE, o[0][3] * F8_ACT_SCALE);
;                     w8.y = pack4_fp8(o[1][0] * F8_ACT_SCALE, o[1][1] * F8_ACT_SCALE, o[1][2] * F8_ACT_SCALE, o[1][3] * F8_ACT_SCALE);
;                     *(u32x2*)((unsigned char*)O + (((size_t)u.pm * (ldo / 128) + (col0 >> 7)) * BM + (ai * HALF + wr * 64 + m * 16 + fr)) * 128 + (col0 & 127)) = w8;
;                 } else
;                 *(u32x4*)(O + (((size_t)u.pm * (ldo / 64) + (col0 >> 6)) * BM + (ai * HALF + wr * 64 + m * 16 + fr)) * 64 + (col0 & 63)) = pack8(o[0], o[1]);
;             }
	v_exp_f32_e32 v192, v192
	v_exp_f32_e32 v193, v193
	v_pk_mul_f32 v[46:47], v[46:47], v[42:43]
	v_pk_fma_f32 v[190:191], v[190:191], v[188:189], v[188:189] op_sel_hi:[1,0,0]
	v_pk_fma_f32 v[192:193], v[192:193], v[188:189], v[188:189] op_sel_hi:[1,0,0]
	v_rcp_f32_e32 v190, v190
	v_rcp_f32_e32 v191, v191
	v_rcp_f32_e32 v192, v192
	v_rcp_f32_e32 v193, v193
	v_pk_mul_f32 v[44:45], v[44:45], v[190:191]
	v_pk_mul_f32 v[46:47], v[46:47], v[192:193]
	v_pk_mul_f32 v[190:191], v[36:37], v[186:187] op_sel_hi:[1,0]
	v_pk_mul_f32 v[192:193], v[38:39], v[186:187] op_sel_hi:[1,0]
	v_pk_mul_f32 v[36:37], v[36:37], v[32:33]
	v_exp_f32_e32 v190, v190
	v_exp_f32_e32 v191, v191
	v_exp_f32_e32 v192, v192
	v_exp_f32_e32 v193, v193
	v_pk_mul_f32 v[38:39], v[38:39], v[34:35]
	v_pk_fma_f32 v[190:191], v[190:191], v[188:189], v[188:189] op_sel_hi:[1,0,0]
	v_pk_fma_f32 v[192:193], v[192:193], v[188:189], v[188:189] op_sel_hi:[1,0,0]
	v_rcp_f32_e32 v190, v190
	v_rcp_f32_e32 v191, v191
	v_rcp_f32_e32 v192, v192
	v_rcp_f32_e32 v193, v193
	v_pk_mul_f32 v[36:37], v[36:37], v[190:191]
	v_pk_mul_f32 v[38:39], v[38:39], v[192:193]
	v_cvt_pk_bf16_f32 v198, v44, v45
	v_cvt_pk_bf16_f32 v199, v46, v47
	v_cvt_pk_bf16_f32 v200, v36, v37
	v_cvt_pk_bf16_f32 v201, v38, v39
	global_store_dwordx4 v[204:205], v[198:201], off offset:-2048
	v_fmamk_f32 v188, v178, 0x3a000000, v145
	v_rsq_f32_e32 v184, v188
	s_nop 0
	v_mul_f32_e32 v184, 0x3a800000, v184
	v_mul_f32_e32 v186, 0xbfb8aa3b, v184
	v_mul_f32_e32 v188, 0x49800000, v188
	v_pk_mul_f32 v[190:191], v[28:29], v[186:187] op_sel_hi:[1,0]
	v_pk_mul_f32 v[192:193], v[30:31], v[186:187] op_sel_hi:[1,0]
	v_pk_mul_f32 v[28:29], v[28:29], v[24:25]
	v_exp_f32_e32 v190, v190
	v_exp_f32_e32 v191, v191
	v_exp_f32_e32 v192, v192
	v_exp_f32_e32 v193, v193
	v_pk_mul_f32 v[30:31], v[30:31], v[26:27]
	v_pk_fma_f32 v[190:191], v[190:191], v[188:189], v[188:189] op_sel_hi:[1,0,0]
	v_pk_fma_f32 v[192:193], v[192:193], v[188:189], v[188:189] op_sel_hi:[1,0,0]
	v_rcp_f32_e32 v190, v190
	v_rcp_f32_e32 v191, v191
	v_rcp_f32_e32 v192, v192
	v_rcp_f32_e32 v193, v193
	v_pk_mul_f32 v[28:29], v[28:29], v[190:191]
	v_pk_mul_f32 v[30:31], v[30:31], v[192:193]
	v_pk_mul_f32 v[190:191], v[20:21], v[186:187] op_sel_hi:[1,0]
	v_pk_mul_f32 v[192:193], v[22:23], v[186:187] op_sel_hi:[1,0]
	v_pk_mul_f32 v[20:21], v[20:21], v[16:17]
	v_exp_f32_e32 v190, v190
	v_exp_f32_e32 v191, v191
	v_exp_f32_e32 v192, v192
	v_exp_f32_e32 v193, v193
	v_pk_mul_f32 v[22:23], v[22:23], v[18:19]
	v_pk_fma_f32 v[190:191], v[190:191], v[188:189], v[188:189] op_sel_hi:[1,0,0]
	v_pk_fma_f32 v[192:193], v[192:193], v[188:189], v[188:189] op_sel_hi:[1,0,0]
	v_rcp_f32_e32 v190, v190
	v_rcp_f32_e32 v191, v191
	v_rcp_f32_e32 v192, v192
	v_rcp_f32_e32 v193, v193
	v_pk_mul_f32 v[20:21], v[20:21], v[190:191]
	v_pk_mul_f32 v[22:23], v[22:23], v[192:193]
	v_cvt_pk_bf16_f32 v194, v28, v29
	v_cvt_pk_bf16_f32 v195, v30, v31
	v_cvt_pk_bf16_f32 v196, v20, v21
	v_cvt_pk_bf16_f32 v197, v22, v23
	global_store_dwordx4 v[204:205], v[194:197], off offset:0
	v_fmamk_f32 v188, v179, 0x3a000000, v145
	v_rsq_f32_e32 v184, v188
	s_nop 0
	v_mul_f32_e32 v184, 0x3a800000, v184
	v_mul_f32_e32 v186, 0xbfb8aa3b, v184
	v_mul_f32_e32 v188, 0x49800000, v188
	v_pk_mul_f32 v[190:191], v[12:13], v[186:187] op_sel_hi:[1,0]
	v_pk_mul_f32 v[192:193], v[14:15], v[186:187] op_sel_hi:[1,0]
	v_pk_mul_f32 v[12:13], v[12:13], v[8:9]
	v_exp_f32_e32 v190, v190
	v_exp_f32_e32 v191, v191
	v_exp_f32_e32 v192, v192
	v_exp_f32_e32 v193, v193
	v_pk_mul_f32 v[14:15], v[14:15], v[10:11]
	v_pk_fma_f32 v[190:191], v[190:191], v[188:189], v[188:189] op_sel_hi:[1,0,0]
	v_pk_fma_f32 v[192:193], v[192:193], v[188:189], v[188:189] op_sel_hi:[1,0,0]
	v_rcp_f32_e32 v190, v190
	v_rcp_f32_e32 v191, v191
	v_rcp_f32_e32 v192, v192
	v_rcp_f32_e32 v193, v193
	v_pk_mul_f32 v[12:13], v[12:13], v[190:191]
	v_pk_mul_f32 v[14:15], v[14:15], v[192:193]
	v_pk_mul_f32 v[190:191], v[4:5], v[186:187] op_sel_hi:[1,0]
	v_pk_mul_f32 v[192:193], v[6:7], v[186:187] op_sel_hi:[1,0]
	v_pk_mul_f32 v[4:5], v[4:5], v[0:1]
	v_exp_f32_e32 v190, v190
	v_exp_f32_e32 v191, v191
	v_exp_f32_e32 v192, v192
	v_exp_f32_e32 v193, v193
	v_pk_mul_f32 v[6:7], v[6:7], v[2:3]
	v_pk_fma_f32 v[190:191], v[190:191], v[188:189], v[188:189] op_sel_hi:[1,0,0]
	v_pk_fma_f32 v[192:193], v[192:193], v[188:189], v[188:189] op_sel_hi:[1,0,0]
	v_rcp_f32_e32 v190, v190
	v_rcp_f32_e32 v191, v191
	v_rcp_f32_e32 v192, v192
	v_rcp_f32_e32 v193, v193
	v_pk_mul_f32 v[4:5], v[4:5], v[190:191]
	v_pk_mul_f32 v[6:7], v[6:7], v[192:193]
	v_cvt_pk_bf16_f32 v198, v12, v13
	v_cvt_pk_bf16_f32 v199, v14, v15
	v_cvt_pk_bf16_f32 v200, v4, v5
	v_cvt_pk_bf16_f32 v201, v6, v7
	global_store_dwordx4 v[204:205], v[198:201], off offset:2048
	s_cbranch_vccnz .LBB0_806
	s_and_b64 vcc, exec, s[16:17]
	s_cbranch_vccnz .LBB0_805
	s_barrier
	s_branch .LBB0_805
